# post-barrier lgkmcnt(0) in front of the MFMA runs dropped in the two-phase loops (the reads are retired before the barrier now)
# baseline (speedup 1.0000x reference)
.LBB0_103:
	s_ashr_i32 s23, s22, 31
	s_lshl_b64 s[2:3], s[22:23], 19
	s_add_u32 s58, s90, s2
	s_addc_u32 s59, s77, s3
	s_and_b64 s[2:3], s[46:47], exec
	s_cselect_b32 s1, s59, s49
	s_cselect_b32 s23, s58, s48
	s_add_u32 s34, s34, 0x3e080
	s_addc_u32 s35, s35, 0
	s_add_u32 s51, s48, 0x100
	v_mov_b32_e32 v2, 0
	s_addc_u32 s52, s49, 0
	s_mov_b32 s53, -2
	s_add_u32 s2, s34, 0xfffc2080
	s_addc_u32 s3, s35, -1
	s_add_i32 s12, 0, 0x10000
	v_add_u32_e32 v110, s12, v179
	ds_read_b128 v[98:101], v110
	ds_read_b128 v[102:105], v110 offset:1024
	ds_read_b128 v[106:109], v110 offset:2048
	ds_read_b128 v[110:113], v110 offset:3072
	s_cmp_eq_u32 s53, 12
	s_cselect_b32 s49, s97, s3
	s_cselect_b32 s48, s96, s2
	s_cselect_b32 s3, s1, s52
	s_cselect_b32 s2, s23, s51
	v_lshl_add_u64 v[174:175], s[34:35], 0, v[170:171]
	s_add_i32 m0, s85, 0xc000
	ds_read_b128 v[114:117], v184
	ds_read_b128 v[118:121], v184 offset:1024
	ds_read_b128 v[122:125], v184 offset:2048
	ds_read_b128 v[126:129], v184 offset:3072
	ds_read_b128 v[186:189], v184 offset:4096
	ds_read_b128 v[190:193], v184 offset:5120
	ds_read_b128 v[194:197], v184 offset:6144
	ds_read_b128 v[198:201], v184 offset:7168
	global_load_lds_dwordx4 v[174:175], off
	v_lshl_add_u64 v[174:175], s[34:35], 0, v[172:173]
	s_add_i32 m0, s85, 0xe000
	s_nop 0
	global_load_lds_dwordx4 v[174:175], off
	s_waitcnt lgkmcnt(8)
	s_add_i32 s54, 0, 0x14000
	v_add_u32_e32 v174, s54, v179
	s_add_i32 s12, s12, s78
	ds_read_b128 v[226:229], v174
	ds_read_b128 v[230:233], v174 offset:1024
	ds_read_b128 v[234:237], v174 offset:2048
	ds_read_b128 v[242:245], v174 offset:3072
	s_waitcnt lgkmcnt(0)
	s_barrier
	v_mfma_f32_16x16x32_bf16 v[158:161], v[98:101], v[114:117], 0
	v_mfma_f32_16x16x32_bf16 v[154:157], v[106:109], v[114:117], 0
	v_mfma_f32_16x16x32_bf16 v[150:153], v[98:101], v[122:125], 0
	v_mfma_f32_16x16x32_bf16 v[146:149], v[106:109], v[122:125], 0
	v_mfma_f32_16x16x32_bf16 v[142:145], v[98:101], v[186:189], 0
	v_mfma_f32_16x16x32_bf16 v[138:141], v[106:109], v[186:189], 0
	v_mfma_f32_16x16x32_bf16 v[134:137], v[98:101], v[194:197], 0
	v_mfma_f32_16x16x32_bf16 v[130:133], v[106:109], v[194:197], 0
	v_mfma_f32_16x16x32_bf16 v[158:161], v[102:105], v[118:121], v[158:161]
	v_mfma_f32_16x16x32_bf16 v[154:157], v[110:113], v[118:121], v[154:157]
	v_mfma_f32_16x16x32_bf16 v[150:153], v[102:105], v[126:129], v[150:153]
	v_mfma_f32_16x16x32_bf16 v[146:149], v[110:113], v[126:129], v[146:149]
	v_mfma_f32_16x16x32_bf16 v[142:145], v[102:105], v[190:193], v[142:145]
	v_mfma_f32_16x16x32_bf16 v[138:141], v[110:113], v[190:193], v[138:141]
	v_mfma_f32_16x16x32_bf16 v[134:137], v[102:105], v[198:201], v[134:137]
	v_mfma_f32_16x16x32_bf16 v[130:133], v[110:113], v[198:201], v[130:133]
	v_mfma_f32_16x16x32_bf16 v[62:65], v[226:229], v[114:117], 0
	v_mfma_f32_16x16x32_bf16 v[58:61], v[234:237], v[114:117], 0
	v_mfma_f32_16x16x32_bf16 v[54:57], v[226:229], v[122:125], 0
	v_mfma_f32_16x16x32_bf16 v[50:53], v[234:237], v[122:125], 0
	v_mfma_f32_16x16x32_bf16 v[46:49], v[226:229], v[186:189], 0
	v_mfma_f32_16x16x32_bf16 v[42:45], v[234:237], v[186:189], 0
	v_mfma_f32_16x16x32_bf16 v[38:41], v[226:229], v[194:197], 0
	v_mfma_f32_16x16x32_bf16 v[34:37], v[234:237], v[194:197], 0
	v_mfma_f32_16x16x32_bf16 v[62:65], v[230:233], v[118:121], v[62:65]
	v_mfma_f32_16x16x32_bf16 v[58:61], v[242:245], v[118:121], v[58:61]
	v_mfma_f32_16x16x32_bf16 v[54:57], v[230:233], v[126:129], v[54:57]
	v_mfma_f32_16x16x32_bf16 v[50:53], v[242:245], v[126:129], v[50:53]
	s_mov_b32 m0, s85
	v_lshl_add_u64 v[248:249], s[48:49], 0, v[162:163]
	v_mfma_f32_16x16x32_bf16 v[46:49], v[230:233], v[190:193], v[46:49]
	v_mfma_f32_16x16x32_bf16 v[42:45], v[242:245], v[190:193], v[42:45]
	v_mfma_f32_16x16x32_bf16 v[38:41], v[230:233], v[198:201], v[38:41]
	v_mfma_f32_16x16x32_bf16 v[34:37], v[242:245], v[198:201], v[34:37]
	s_barrier
	ds_read_b128 v[114:117], v184 offset:16384
	ds_read_b128 v[118:121], v184 offset:17408
	ds_read_b128 v[122:125], v184 offset:18432
	ds_read_b128 v[126:129], v184 offset:19456
	ds_read_b128 v[186:189], v184 offset:20480
	ds_read_b128 v[190:193], v184 offset:21504
	ds_read_b128 v[194:197], v184 offset:22528
	ds_read_b128 v[198:201], v184 offset:23552
	global_load_lds_dwordx4 v[248:249], off
	v_lshl_add_u64 v[250:251], s[48:49], 0, v[164:165]
	s_mov_b32 m0, s82
	s_nop 0
	global_load_lds_dwordx4 v[250:251], off
	v_lshl_add_u64 v[174:175], s[2:3], 0, v[0:1]
	s_mov_b32 m0, s12
	v_lshl_add_u64 v[246:247], s[2:3], 0, v[166:167]
	global_load_lds_dwordx4 v[174:175], off
	s_add_i32 m0, s12, 0x2000
	s_nop 0
	global_load_lds_dwordx4 v[246:247], off
	s_add_u32 s12, s2, 0x40000
	s_addc_u32 s13, s3, 0
	s_add_i32 s54, s54, s78
	v_lshl_add_u64 v[174:175], s[12:13], 0, v[0:1]
	s_mov_b32 m0, s54
	s_nop 0
	global_load_lds_dwordx4 v[174:175], off
	v_lshl_add_u64 v[174:175], s[12:13], 0, v[166:167]
	s_add_i32 m0, s54, 0x2000
	s_nop 0
	global_load_lds_dwordx4 v[174:175], off
	s_waitcnt vmcnt(6)
	s_waitcnt lgkmcnt(0)
	s_barrier
	v_mfma_f32_16x16x32_bf16 v[94:97], v[98:101], v[114:117], 0
	v_mfma_f32_16x16x32_bf16 v[90:93], v[106:109], v[114:117], 0
	v_mfma_f32_16x16x32_bf16 v[86:89], v[98:101], v[122:125], 0
	v_mfma_f32_16x16x32_bf16 v[82:85], v[106:109], v[122:125], 0
	v_mfma_f32_16x16x32_bf16 v[78:81], v[98:101], v[186:189], 0
	v_mfma_f32_16x16x32_bf16 v[74:77], v[106:109], v[186:189], 0
	v_mfma_f32_16x16x32_bf16 v[70:73], v[98:101], v[194:197], 0
	v_mfma_f32_16x16x32_bf16 v[66:69], v[106:109], v[194:197], 0
	v_mfma_f32_16x16x32_bf16 v[94:97], v[102:105], v[118:121], v[94:97]
	v_mfma_f32_16x16x32_bf16 v[90:93], v[110:113], v[118:121], v[90:93]
	v_mfma_f32_16x16x32_bf16 v[86:89], v[102:105], v[126:129], v[86:89]
	v_mfma_f32_16x16x32_bf16 v[82:85], v[110:113], v[126:129], v[82:85]
	v_mfma_f32_16x16x32_bf16 v[78:81], v[102:105], v[190:193], v[78:81]
	v_mfma_f32_16x16x32_bf16 v[74:77], v[110:113], v[190:193], v[74:77]
	v_mfma_f32_16x16x32_bf16 v[70:73], v[102:105], v[198:201], v[70:73]
	v_mfma_f32_16x16x32_bf16 v[66:69], v[110:113], v[198:201], v[66:69]
	v_mfma_f32_16x16x32_bf16 v[30:33], v[226:229], v[114:117], 0
	v_mfma_f32_16x16x32_bf16 v[26:29], v[234:237], v[114:117], 0
	v_mfma_f32_16x16x32_bf16 v[22:25], v[226:229], v[122:125], 0
	v_mfma_f32_16x16x32_bf16 v[18:21], v[234:237], v[122:125], 0
	v_mfma_f32_16x16x32_bf16 v[14:17], v[226:229], v[186:189], 0
	v_mfma_f32_16x16x32_bf16 v[10:13], v[234:237], v[186:189], 0
	v_mfma_f32_16x16x32_bf16 v[6:9], v[226:229], v[194:197], 0
	v_mfma_f32_16x16x32_bf16 v[2:5], v[234:237], v[194:197], 0
	v_mfma_f32_16x16x32_bf16 v[30:33], v[230:233], v[118:121], v[30:33]
	v_mfma_f32_16x16x32_bf16 v[26:29], v[242:245], v[118:121], v[26:29]
	v_mfma_f32_16x16x32_bf16 v[22:25], v[230:233], v[126:129], v[22:25]
	v_mfma_f32_16x16x32_bf16 v[18:21], v[242:245], v[126:129], v[18:21]
	s_add_i32 s54, 0, 0x18000
	v_add_u32_e32 v110, s54, v179
	v_mfma_f32_16x16x32_bf16 v[14:17], v[230:233], v[190:193], v[14:17]
	v_mfma_f32_16x16x32_bf16 v[10:13], v[242:245], v[190:193], v[10:13]
	v_mfma_f32_16x16x32_bf16 v[6:9], v[230:233], v[198:201], v[6:9]
	v_mfma_f32_16x16x32_bf16 v[2:5], v[242:245], v[198:201], v[2:5]
	s_barrier
	ds_read_b128 v[98:101], v110
	ds_read_b128 v[102:105], v110 offset:1024
	ds_read_b128 v[106:109], v110 offset:2048
	ds_read_b128 v[110:113], v110 offset:3072
	s_add_u32 s12, s48, 0x3e000
	s_addc_u32 s13, s49, 0
	s_mov_b32 m0, s89
	v_lshl_add_u64 v[226:227], s[12:13], 0, v[162:163]
	ds_read_b128 v[114:117], v184 offset:32768
	ds_read_b128 v[118:121], v184 offset:33792
	ds_read_b128 v[122:125], v184 offset:34816
	ds_read_b128 v[126:129], v184 offset:35840
	ds_read_b128 v[186:189], v184 offset:36864
	ds_read_b128 v[190:193], v184 offset:37888
	ds_read_b128 v[194:197], v184 offset:38912
	ds_read_b128 v[198:201], v184 offset:39936
	global_load_lds_dwordx4 v[226:227], off
	v_lshl_add_u64 v[226:227], s[12:13], 0, v[164:165]
	s_mov_b32 m0, s91
	s_nop 0
	global_load_lds_dwordx4 v[226:227], off
	s_waitcnt lgkmcnt(8)
	s_add_i32 s12, 0, 0x1c000
	s_add_i32 s13, s54, s78
	v_add_u32_e32 v242, s12, v179
	ds_read_b128 v[226:229], v242
	ds_read_b128 v[230:233], v242 offset:1024
	ds_read_b128 v[234:237], v242 offset:2048
	ds_read_b128 v[242:245], v242 offset:3072
	s_waitcnt lgkmcnt(0)
	s_barrier
	s_nop 0
	v_mfma_f32_16x16x32_bf16 v[158:161], v[98:101], v[114:117], v[158:161]
	v_mfma_f32_16x16x32_bf16 v[154:157], v[106:109], v[114:117], v[154:157]
	v_mfma_f32_16x16x32_bf16 v[150:153], v[98:101], v[122:125], v[150:153]
	v_mfma_f32_16x16x32_bf16 v[146:149], v[106:109], v[122:125], v[146:149]
	v_mfma_f32_16x16x32_bf16 v[142:145], v[98:101], v[186:189], v[142:145]
	v_mfma_f32_16x16x32_bf16 v[138:141], v[106:109], v[186:189], v[138:141]
	v_mfma_f32_16x16x32_bf16 v[134:137], v[98:101], v[194:197], v[134:137]
	v_mfma_f32_16x16x32_bf16 v[130:133], v[106:109], v[194:197], v[130:133]
	v_mfma_f32_16x16x32_bf16 v[158:161], v[102:105], v[118:121], v[158:161]
	v_mfma_f32_16x16x32_bf16 v[154:157], v[110:113], v[118:121], v[154:157]
	v_mfma_f32_16x16x32_bf16 v[150:153], v[102:105], v[126:129], v[150:153]
	v_mfma_f32_16x16x32_bf16 v[146:149], v[110:113], v[126:129], v[146:149]
	v_mfma_f32_16x16x32_bf16 v[142:145], v[102:105], v[190:193], v[142:145]
	v_mfma_f32_16x16x32_bf16 v[138:141], v[110:113], v[190:193], v[138:141]
	v_mfma_f32_16x16x32_bf16 v[134:137], v[102:105], v[198:201], v[134:137]
	v_mfma_f32_16x16x32_bf16 v[130:133], v[110:113], v[198:201], v[130:133]
	v_mfma_f32_16x16x32_bf16 v[62:65], v[226:229], v[114:117], v[62:65]
	v_mfma_f32_16x16x32_bf16 v[58:61], v[234:237], v[114:117], v[58:61]
	v_mfma_f32_16x16x32_bf16 v[54:57], v[226:229], v[122:125], v[54:57]
	v_mfma_f32_16x16x32_bf16 v[50:53], v[234:237], v[122:125], v[50:53]
	v_mfma_f32_16x16x32_bf16 v[46:49], v[226:229], v[186:189], v[46:49]
	v_mfma_f32_16x16x32_bf16 v[42:45], v[234:237], v[186:189], v[42:45]
	v_mfma_f32_16x16x32_bf16 v[38:41], v[226:229], v[194:197], v[38:41]
	v_mfma_f32_16x16x32_bf16 v[34:37], v[234:237], v[194:197], v[34:37]
	v_mfma_f32_16x16x32_bf16 v[62:65], v[230:233], v[118:121], v[62:65]
	v_mfma_f32_16x16x32_bf16 v[58:61], v[242:245], v[118:121], v[58:61]
	v_mfma_f32_16x16x32_bf16 v[54:57], v[230:233], v[126:129], v[54:57]
	v_mfma_f32_16x16x32_bf16 v[50:53], v[242:245], v[126:129], v[50:53]
	s_mov_b32 m0, s79
	v_lshl_add_u64 v[174:175], v[248:249], 0, s[20:21]
	v_mfma_f32_16x16x32_bf16 v[46:49], v[230:233], v[190:193], v[46:49]
	v_mfma_f32_16x16x32_bf16 v[42:45], v[242:245], v[190:193], v[42:45]
	v_mfma_f32_16x16x32_bf16 v[38:41], v[230:233], v[198:201], v[38:41]
	v_mfma_f32_16x16x32_bf16 v[34:37], v[242:245], v[198:201], v[34:37]
	s_barrier
	ds_read_b128 v[114:117], v184 offset:49152
	ds_read_b128 v[118:121], v184 offset:50176
	ds_read_b128 v[122:125], v184 offset:51200
	ds_read_b128 v[126:129], v184 offset:52224
	ds_read_b128 v[186:189], v184 offset:53248
	ds_read_b128 v[190:193], v184 offset:54272
	ds_read_b128 v[194:197], v184 offset:55296
	ds_read_b128 v[198:201], v184 offset:56320
	global_load_lds_dwordx4 v[174:175], off
	v_lshl_add_u64 v[174:175], v[250:251], 0, s[20:21]
	s_mov_b32 m0, s87
	s_nop 0
	global_load_lds_dwordx4 v[174:175], off
	v_lshl_add_u64 v[174:175], s[2:3], 0, v[0:1]
	v_lshl_add_u64 v[174:175], v[174:175], 0, s[20:21]
	s_mov_b32 m0, s13
	s_nop 0
	global_load_lds_dwordx4 v[174:175], off
	v_lshl_add_u64 v[174:175], v[246:247], 0, s[20:21]
	s_add_i32 m0, s13, 0x2000
	s_nop 0
	global_load_lds_dwordx4 v[174:175], off
	s_add_u32 s2, s2, 0x40080
	s_addc_u32 s3, s3, 0
	s_add_i32 s12, s12, s78
	v_lshl_add_u64 v[174:175], s[2:3], 0, v[0:1]
	s_mov_b32 m0, s12
	s_nop 0
	global_load_lds_dwordx4 v[174:175], off
	v_lshl_add_u64 v[174:175], s[2:3], 0, v[166:167]
	s_add_i32 m0, s12, 0x2000
	s_nop 0
	global_load_lds_dwordx4 v[174:175], off
	s_waitcnt vmcnt(6)
	s_waitcnt lgkmcnt(0)
	s_barrier
	s_nop 0
	v_mfma_f32_16x16x32_bf16 v[94:97], v[98:101], v[114:117], v[94:97]
	v_mfma_f32_16x16x32_bf16 v[90:93], v[106:109], v[114:117], v[90:93]
	v_mfma_f32_16x16x32_bf16 v[86:89], v[98:101], v[122:125], v[86:89]
	v_mfma_f32_16x16x32_bf16 v[82:85], v[106:109], v[122:125], v[82:85]
	v_mfma_f32_16x16x32_bf16 v[78:81], v[98:101], v[186:189], v[78:81]
	v_mfma_f32_16x16x32_bf16 v[74:77], v[106:109], v[186:189], v[74:77]
	v_mfma_f32_16x16x32_bf16 v[70:73], v[98:101], v[194:197], v[70:73]
	v_mfma_f32_16x16x32_bf16 v[66:69], v[106:109], v[194:197], v[66:69]
	v_mfma_f32_16x16x32_bf16 v[94:97], v[102:105], v[118:121], v[94:97]
	v_mfma_f32_16x16x32_bf16 v[90:93], v[110:113], v[118:121], v[90:93]
	v_mfma_f32_16x16x32_bf16 v[86:89], v[102:105], v[126:129], v[86:89]
	v_mfma_f32_16x16x32_bf16 v[82:85], v[110:113], v[126:129], v[82:85]
	v_mfma_f32_16x16x32_bf16 v[78:81], v[102:105], v[190:193], v[78:81]
	v_mfma_f32_16x16x32_bf16 v[74:77], v[110:113], v[190:193], v[74:77]
	v_mfma_f32_16x16x32_bf16 v[70:73], v[102:105], v[198:201], v[70:73]
	v_mfma_f32_16x16x32_bf16 v[66:69], v[110:113], v[198:201], v[66:69]
	v_mfma_f32_16x16x32_bf16 v[30:33], v[226:229], v[114:117], v[30:33]
	v_mfma_f32_16x16x32_bf16 v[26:29], v[234:237], v[114:117], v[26:29]
	v_mfma_f32_16x16x32_bf16 v[22:25], v[226:229], v[122:125], v[22:25]
	v_mfma_f32_16x16x32_bf16 v[18:21], v[234:237], v[122:125], v[18:21]
	v_mfma_f32_16x16x32_bf16 v[14:17], v[226:229], v[186:189], v[14:17]
	v_mfma_f32_16x16x32_bf16 v[10:13], v[234:237], v[186:189], v[10:13]
	v_mfma_f32_16x16x32_bf16 v[6:9], v[226:229], v[194:197], v[6:9]
	v_mfma_f32_16x16x32_bf16 v[2:5], v[234:237], v[194:197], v[2:5]
	v_mfma_f32_16x16x32_bf16 v[30:33], v[230:233], v[118:121], v[30:33]
	v_mfma_f32_16x16x32_bf16 v[26:29], v[242:245], v[118:121], v[26:29]
	v_mfma_f32_16x16x32_bf16 v[22:25], v[230:233], v[126:129], v[22:25]
	v_mfma_f32_16x16x32_bf16 v[18:21], v[242:245], v[126:129], v[18:21]
	s_add_i32 s53, s53, 2
	s_add_u32 s34, s34, 0x100
	s_addc_u32 s35, s35, 0
	s_add_u32 s51, s51, 0x100
	s_addc_u32 s52, s52, 0
	s_cmp_gt_u32 s53, 13
	v_mfma_f32_16x16x32_bf16 v[14:17], v[230:233], v[190:193], v[14:17]
	v_mfma_f32_16x16x32_bf16 v[10:13], v[242:245], v[190:193], v[10:13]
	v_mfma_f32_16x16x32_bf16 v[6:9], v[230:233], v[198:201], v[6:9]
	v_mfma_f32_16x16x32_bf16 v[2:5], v[242:245], v[198:201], v[2:5]
	s_barrier
	s_cbranch_scc1 .Lpeel_x_0
.LBB0_104:
	s_add_u32 s2, s34, 0xfffc2080
	s_addc_u32 s3, s35, -1
	s_add_i32 s12, 0, 0x10000
	v_add_u32_e32 v110, s12, v179
	ds_read_b128 v[98:101], v110
	ds_read_b128 v[102:105], v110 offset:1024
	ds_read_b128 v[106:109], v110 offset:2048
	ds_read_b128 v[110:113], v110 offset:3072
	s_cmp_eq_u32 s53, 12
	s_cselect_b32 s49, s97, s3
	s_cselect_b32 s48, s96, s2
	s_cselect_b32 s3, s1, s52
	s_cselect_b32 s2, s23, s51
	v_lshl_add_u64 v[174:175], s[34:35], 0, v[170:171]
	s_add_i32 m0, s85, 0xc000
	ds_read_b128 v[114:117], v184
	ds_read_b128 v[118:121], v184 offset:1024
	ds_read_b128 v[122:125], v184 offset:2048
	ds_read_b128 v[126:129], v184 offset:3072
	ds_read_b128 v[186:189], v184 offset:4096
	ds_read_b128 v[190:193], v184 offset:5120
	ds_read_b128 v[194:197], v184 offset:6144
	ds_read_b128 v[198:201], v184 offset:7168
	global_load_lds_dwordx4 v[174:175], off
	v_lshl_add_u64 v[174:175], s[34:35], 0, v[172:173]
	s_add_i32 m0, s85, 0xe000
	s_nop 0
	global_load_lds_dwordx4 v[174:175], off
	s_waitcnt lgkmcnt(8)
	s_add_i32 s54, 0, 0x14000
	v_add_u32_e32 v174, s54, v179
	s_add_i32 s12, s12, s78
	ds_read_b128 v[226:229], v174
	ds_read_b128 v[230:233], v174 offset:1024
	ds_read_b128 v[234:237], v174 offset:2048
	ds_read_b128 v[242:245], v174 offset:3072
	s_waitcnt lgkmcnt(0)
	s_barrier
	s_nop 0
	v_mfma_f32_16x16x32_bf16 v[158:161], v[98:101], v[114:117], v[158:161]
	v_mfma_f32_16x16x32_bf16 v[154:157], v[106:109], v[114:117], v[154:157]
	v_mfma_f32_16x16x32_bf16 v[150:153], v[98:101], v[122:125], v[150:153]
	v_mfma_f32_16x16x32_bf16 v[146:149], v[106:109], v[122:125], v[146:149]
	v_mfma_f32_16x16x32_bf16 v[142:145], v[98:101], v[186:189], v[142:145]
	v_mfma_f32_16x16x32_bf16 v[138:141], v[106:109], v[186:189], v[138:141]
	v_mfma_f32_16x16x32_bf16 v[134:137], v[98:101], v[194:197], v[134:137]
	v_mfma_f32_16x16x32_bf16 v[130:133], v[106:109], v[194:197], v[130:133]
	v_mfma_f32_16x16x32_bf16 v[158:161], v[102:105], v[118:121], v[158:161]
	v_mfma_f32_16x16x32_bf16 v[154:157], v[110:113], v[118:121], v[154:157]
	v_mfma_f32_16x16x32_bf16 v[150:153], v[102:105], v[126:129], v[150:153]
	v_mfma_f32_16x16x32_bf16 v[146:149], v[110:113], v[126:129], v[146:149]
	v_mfma_f32_16x16x32_bf16 v[142:145], v[102:105], v[190:193], v[142:145]
	v_mfma_f32_16x16x32_bf16 v[138:141], v[110:113], v[190:193], v[138:141]
	v_mfma_f32_16x16x32_bf16 v[134:137], v[102:105], v[198:201], v[134:137]
	v_mfma_f32_16x16x32_bf16 v[130:133], v[110:113], v[198:201], v[130:133]
	v_mfma_f32_16x16x32_bf16 v[62:65], v[226:229], v[114:117], v[62:65]
	v_mfma_f32_16x16x32_bf16 v[58:61], v[234:237], v[114:117], v[58:61]
	v_mfma_f32_16x16x32_bf16 v[54:57], v[226:229], v[122:125], v[54:57]
	v_mfma_f32_16x16x32_bf16 v[50:53], v[234:237], v[122:125], v[50:53]
	v_mfma_f32_16x16x32_bf16 v[46:49], v[226:229], v[186:189], v[46:49]
	v_mfma_f32_16x16x32_bf16 v[42:45], v[234:237], v[186:189], v[42:45]
	v_mfma_f32_16x16x32_bf16 v[38:41], v[226:229], v[194:197], v[38:41]
	v_mfma_f32_16x16x32_bf16 v[34:37], v[234:237], v[194:197], v[34:37]
	v_mfma_f32_16x16x32_bf16 v[62:65], v[230:233], v[118:121], v[62:65]
	v_mfma_f32_16x16x32_bf16 v[58:61], v[242:245], v[118:121], v[58:61]
	v_mfma_f32_16x16x32_bf16 v[54:57], v[230:233], v[126:129], v[54:57]
	v_mfma_f32_16x16x32_bf16 v[50:53], v[242:245], v[126:129], v[50:53]
	s_mov_b32 m0, s85
	v_lshl_add_u64 v[248:249], s[48:49], 0, v[162:163]
	v_mfma_f32_16x16x32_bf16 v[46:49], v[230:233], v[190:193], v[46:49]
	v_mfma_f32_16x16x32_bf16 v[42:45], v[242:245], v[190:193], v[42:45]
	v_mfma_f32_16x16x32_bf16 v[38:41], v[230:233], v[198:201], v[38:41]
	v_mfma_f32_16x16x32_bf16 v[34:37], v[242:245], v[198:201], v[34:37]
	s_barrier
	ds_read_b128 v[114:117], v184 offset:16384
	ds_read_b128 v[118:121], v184 offset:17408
	ds_read_b128 v[122:125], v184 offset:18432
	ds_read_b128 v[126:129], v184 offset:19456
	ds_read_b128 v[186:189], v184 offset:20480
	ds_read_b128 v[190:193], v184 offset:21504
	ds_read_b128 v[194:197], v184 offset:22528
	ds_read_b128 v[198:201], v184 offset:23552
	global_load_lds_dwordx4 v[248:249], off
	v_lshl_add_u64 v[250:251], s[48:49], 0, v[164:165]
	s_mov_b32 m0, s82
	s_nop 0
	global_load_lds_dwordx4 v[250:251], off
	v_lshl_add_u64 v[174:175], s[2:3], 0, v[0:1]
	s_mov_b32 m0, s12
	v_lshl_add_u64 v[246:247], s[2:3], 0, v[166:167]
	global_load_lds_dwordx4 v[174:175], off
	s_add_i32 m0, s12, 0x2000
	s_nop 0
	global_load_lds_dwordx4 v[246:247], off
	s_add_u32 s12, s2, 0x40000
	s_addc_u32 s13, s3, 0
	s_add_i32 s54, s54, s78
	v_lshl_add_u64 v[174:175], s[12:13], 0, v[0:1]
	s_mov_b32 m0, s54
	s_nop 0
	global_load_lds_dwordx4 v[174:175], off
	v_lshl_add_u64 v[174:175], s[12:13], 0, v[166:167]
	s_add_i32 m0, s54, 0x2000
	s_nop 0
	global_load_lds_dwordx4 v[174:175], off
	s_waitcnt vmcnt(6)
	s_waitcnt lgkmcnt(0)
	s_barrier
	v_mfma_f32_16x16x32_bf16 v[94:97], v[98:101], v[114:117], v[94:97]
	v_mfma_f32_16x16x32_bf16 v[90:93], v[106:109], v[114:117], v[90:93]
	v_mfma_f32_16x16x32_bf16 v[86:89], v[98:101], v[122:125], v[86:89]
	v_mfma_f32_16x16x32_bf16 v[82:85], v[106:109], v[122:125], v[82:85]
	v_mfma_f32_16x16x32_bf16 v[78:81], v[98:101], v[186:189], v[78:81]
	v_mfma_f32_16x16x32_bf16 v[74:77], v[106:109], v[186:189], v[74:77]
	v_mfma_f32_16x16x32_bf16 v[70:73], v[98:101], v[194:197], v[70:73]
	v_mfma_f32_16x16x32_bf16 v[66:69], v[106:109], v[194:197], v[66:69]
	v_mfma_f32_16x16x32_bf16 v[94:97], v[102:105], v[118:121], v[94:97]
	v_mfma_f32_16x16x32_bf16 v[90:93], v[110:113], v[118:121], v[90:93]
	v_mfma_f32_16x16x32_bf16 v[86:89], v[102:105], v[126:129], v[86:89]
	v_mfma_f32_16x16x32_bf16 v[82:85], v[110:113], v[126:129], v[82:85]
	v_mfma_f32_16x16x32_bf16 v[78:81], v[102:105], v[190:193], v[78:81]
	v_mfma_f32_16x16x32_bf16 v[74:77], v[110:113], v[190:193], v[74:77]
	v_mfma_f32_16x16x32_bf16 v[70:73], v[102:105], v[198:201], v[70:73]
	v_mfma_f32_16x16x32_bf16 v[66:69], v[110:113], v[198:201], v[66:69]
	v_mfma_f32_16x16x32_bf16 v[30:33], v[226:229], v[114:117], v[30:33]
	v_mfma_f32_16x16x32_bf16 v[26:29], v[234:237], v[114:117], v[26:29]
	v_mfma_f32_16x16x32_bf16 v[22:25], v[226:229], v[122:125], v[22:25]
	v_mfma_f32_16x16x32_bf16 v[18:21], v[234:237], v[122:125], v[18:21]
	v_mfma_f32_16x16x32_bf16 v[14:17], v[226:229], v[186:189], v[14:17]
	v_mfma_f32_16x16x32_bf16 v[10:13], v[234:237], v[186:189], v[10:13]
	v_mfma_f32_16x16x32_bf16 v[6:9], v[226:229], v[194:197], v[6:9]
	v_mfma_f32_16x16x32_bf16 v[2:5], v[234:237], v[194:197], v[2:5]
	v_mfma_f32_16x16x32_bf16 v[30:33], v[230:233], v[118:121], v[30:33]
	v_mfma_f32_16x16x32_bf16 v[26:29], v[242:245], v[118:121], v[26:29]
	v_mfma_f32_16x16x32_bf16 v[22:25], v[230:233], v[126:129], v[22:25]
	v_mfma_f32_16x16x32_bf16 v[18:21], v[242:245], v[126:129], v[18:21]
	s_add_i32 s54, 0, 0x18000
	v_add_u32_e32 v110, s54, v179
	v_mfma_f32_16x16x32_bf16 v[14:17], v[230:233], v[190:193], v[14:17]
	v_mfma_f32_16x16x32_bf16 v[10:13], v[242:245], v[190:193], v[10:13]
	v_mfma_f32_16x16x32_bf16 v[6:9], v[230:233], v[198:201], v[6:9]
	v_mfma_f32_16x16x32_bf16 v[2:5], v[242:245], v[198:201], v[2:5]
	s_barrier
	ds_read_b128 v[98:101], v110
	ds_read_b128 v[102:105], v110 offset:1024
	ds_read_b128 v[106:109], v110 offset:2048
	ds_read_b128 v[110:113], v110 offset:3072
	s_add_u32 s12, s48, 0x3e000
	s_addc_u32 s13, s49, 0
	s_mov_b32 m0, s89
	v_lshl_add_u64 v[226:227], s[12:13], 0, v[162:163]
	ds_read_b128 v[114:117], v184 offset:32768
	ds_read_b128 v[118:121], v184 offset:33792
	ds_read_b128 v[122:125], v184 offset:34816
	ds_read_b128 v[126:129], v184 offset:35840
	ds_read_b128 v[186:189], v184 offset:36864
	ds_read_b128 v[190:193], v184 offset:37888
	ds_read_b128 v[194:197], v184 offset:38912
	ds_read_b128 v[198:201], v184 offset:39936
	global_load_lds_dwordx4 v[226:227], off
	v_lshl_add_u64 v[226:227], s[12:13], 0, v[164:165]
	s_mov_b32 m0, s91
	s_nop 0
	global_load_lds_dwordx4 v[226:227], off
	s_waitcnt lgkmcnt(8)
	s_add_i32 s12, 0, 0x1c000
	s_add_i32 s13, s54, s78
	v_add_u32_e32 v242, s12, v179
	ds_read_b128 v[226:229], v242
	ds_read_b128 v[230:233], v242 offset:1024
	ds_read_b128 v[234:237], v242 offset:2048
	ds_read_b128 v[242:245], v242 offset:3072
	s_waitcnt lgkmcnt(0)
	s_barrier
	s_nop 0
	v_mfma_f32_16x16x32_bf16 v[158:161], v[98:101], v[114:117], v[158:161]
	v_mfma_f32_16x16x32_bf16 v[154:157], v[106:109], v[114:117], v[154:157]
	v_mfma_f32_16x16x32_bf16 v[150:153], v[98:101], v[122:125], v[150:153]
	v_mfma_f32_16x16x32_bf16 v[146:149], v[106:109], v[122:125], v[146:149]
	v_mfma_f32_16x16x32_bf16 v[142:145], v[98:101], v[186:189], v[142:145]
	v_mfma_f32_16x16x32_bf16 v[138:141], v[106:109], v[186:189], v[138:141]
	v_mfma_f32_16x16x32_bf16 v[134:137], v[98:101], v[194:197], v[134:137]
	v_mfma_f32_16x16x32_bf16 v[130:133], v[106:109], v[194:197], v[130:133]
	v_mfma_f32_16x16x32_bf16 v[158:161], v[102:105], v[118:121], v[158:161]
	v_mfma_f32_16x16x32_bf16 v[154:157], v[110:113], v[118:121], v[154:157]
	v_mfma_f32_16x16x32_bf16 v[150:153], v[102:105], v[126:129], v[150:153]
	v_mfma_f32_16x16x32_bf16 v[146:149], v[110:113], v[126:129], v[146:149]
	v_mfma_f32_16x16x32_bf16 v[142:145], v[102:105], v[190:193], v[142:145]
	v_mfma_f32_16x16x32_bf16 v[138:141], v[110:113], v[190:193], v[138:141]
	v_mfma_f32_16x16x32_bf16 v[134:137], v[102:105], v[198:201], v[134:137]
	v_mfma_f32_16x16x32_bf16 v[130:133], v[110:113], v[198:201], v[130:133]
	v_mfma_f32_16x16x32_bf16 v[62:65], v[226:229], v[114:117], v[62:65]
	v_mfma_f32_16x16x32_bf16 v[58:61], v[234:237], v[114:117], v[58:61]
	v_mfma_f32_16x16x32_bf16 v[54:57], v[226:229], v[122:125], v[54:57]
	v_mfma_f32_16x16x32_bf16 v[50:53], v[234:237], v[122:125], v[50:53]
	v_mfma_f32_16x16x32_bf16 v[46:49], v[226:229], v[186:189], v[46:49]
	v_mfma_f32_16x16x32_bf16 v[42:45], v[234:237], v[186:189], v[42:45]
	v_mfma_f32_16x16x32_bf16 v[38:41], v[226:229], v[194:197], v[38:41]
	v_mfma_f32_16x16x32_bf16 v[34:37], v[234:237], v[194:197], v[34:37]
	v_mfma_f32_16x16x32_bf16 v[62:65], v[230:233], v[118:121], v[62:65]
	v_mfma_f32_16x16x32_bf16 v[58:61], v[242:245], v[118:121], v[58:61]
	v_mfma_f32_16x16x32_bf16 v[54:57], v[230:233], v[126:129], v[54:57]
	v_mfma_f32_16x16x32_bf16 v[50:53], v[242:245], v[126:129], v[50:53]
	s_mov_b32 m0, s79
	v_lshl_add_u64 v[174:175], v[248:249], 0, s[20:21]
	v_mfma_f32_16x16x32_bf16 v[46:49], v[230:233], v[190:193], v[46:49]
	v_mfma_f32_16x16x32_bf16 v[42:45], v[242:245], v[190:193], v[42:45]
	v_mfma_f32_16x16x32_bf16 v[38:41], v[230:233], v[198:201], v[38:41]
	v_mfma_f32_16x16x32_bf16 v[34:37], v[242:245], v[198:201], v[34:37]
	s_barrier
	ds_read_b128 v[114:117], v184 offset:49152
	ds_read_b128 v[118:121], v184 offset:50176
	ds_read_b128 v[122:125], v184 offset:51200
	ds_read_b128 v[126:129], v184 offset:52224
	ds_read_b128 v[186:189], v184 offset:53248
	ds_read_b128 v[190:193], v184 offset:54272
	ds_read_b128 v[194:197], v184 offset:55296
	ds_read_b128 v[198:201], v184 offset:56320
	global_load_lds_dwordx4 v[174:175], off
	v_lshl_add_u64 v[174:175], v[250:251], 0, s[20:21]
	s_mov_b32 m0, s87
	s_nop 0
	global_load_lds_dwordx4 v[174:175], off
	v_lshl_add_u64 v[174:175], s[2:3], 0, v[0:1]
	v_lshl_add_u64 v[174:175], v[174:175], 0, s[20:21]
	s_mov_b32 m0, s13
	s_nop 0
	global_load_lds_dwordx4 v[174:175], off
	v_lshl_add_u64 v[174:175], v[246:247], 0, s[20:21]
	s_add_i32 m0, s13, 0x2000
	s_nop 0
	global_load_lds_dwordx4 v[174:175], off
	s_add_u32 s2, s2, 0x40080
	s_addc_u32 s3, s3, 0
	s_add_i32 s12, s12, s78
	v_lshl_add_u64 v[174:175], s[2:3], 0, v[0:1]
	s_mov_b32 m0, s12
	s_nop 0
	global_load_lds_dwordx4 v[174:175], off
	v_lshl_add_u64 v[174:175], s[2:3], 0, v[166:167]
	s_add_i32 m0, s12, 0x2000
	s_nop 0
	global_load_lds_dwordx4 v[174:175], off
	s_waitcnt vmcnt(6)
	s_waitcnt lgkmcnt(0)
	s_barrier
	s_nop 0
	v_mfma_f32_16x16x32_bf16 v[94:97], v[98:101], v[114:117], v[94:97]
	v_mfma_f32_16x16x32_bf16 v[90:93], v[106:109], v[114:117], v[90:93]
	v_mfma_f32_16x16x32_bf16 v[86:89], v[98:101], v[122:125], v[86:89]
	v_mfma_f32_16x16x32_bf16 v[82:85], v[106:109], v[122:125], v[82:85]
	v_mfma_f32_16x16x32_bf16 v[78:81], v[98:101], v[186:189], v[78:81]
	v_mfma_f32_16x16x32_bf16 v[74:77], v[106:109], v[186:189], v[74:77]
	v_mfma_f32_16x16x32_bf16 v[70:73], v[98:101], v[194:197], v[70:73]
	v_mfma_f32_16x16x32_bf16 v[66:69], v[106:109], v[194:197], v[66:69]
	v_mfma_f32_16x16x32_bf16 v[94:97], v[102:105], v[118:121], v[94:97]
	v_mfma_f32_16x16x32_bf16 v[90:93], v[110:113], v[118:121], v[90:93]
	v_mfma_f32_16x16x32_bf16 v[86:89], v[102:105], v[126:129], v[86:89]
	v_mfma_f32_16x16x32_bf16 v[82:85], v[110:113], v[126:129], v[82:85]
	v_mfma_f32_16x16x32_bf16 v[78:81], v[102:105], v[190:193], v[78:81]
	v_mfma_f32_16x16x32_bf16 v[74:77], v[110:113], v[190:193], v[74:77]
	v_mfma_f32_16x16x32_bf16 v[70:73], v[102:105], v[198:201], v[70:73]
	v_mfma_f32_16x16x32_bf16 v[66:69], v[110:113], v[198:201], v[66:69]
	v_mfma_f32_16x16x32_bf16 v[30:33], v[226:229], v[114:117], v[30:33]
	v_mfma_f32_16x16x32_bf16 v[26:29], v[234:237], v[114:117], v[26:29]
	v_mfma_f32_16x16x32_bf16 v[22:25], v[226:229], v[122:125], v[22:25]
	v_mfma_f32_16x16x32_bf16 v[18:21], v[234:237], v[122:125], v[18:21]
	v_mfma_f32_16x16x32_bf16 v[14:17], v[226:229], v[186:189], v[14:17]
	v_mfma_f32_16x16x32_bf16 v[10:13], v[234:237], v[186:189], v[10:13]
	v_mfma_f32_16x16x32_bf16 v[6:9], v[226:229], v[194:197], v[6:9]
	v_mfma_f32_16x16x32_bf16 v[2:5], v[234:237], v[194:197], v[2:5]
	v_mfma_f32_16x16x32_bf16 v[30:33], v[230:233], v[118:121], v[30:33]
	v_mfma_f32_16x16x32_bf16 v[26:29], v[242:245], v[118:121], v[26:29]
	v_mfma_f32_16x16x32_bf16 v[22:25], v[230:233], v[126:129], v[22:25]
	v_mfma_f32_16x16x32_bf16 v[18:21], v[242:245], v[126:129], v[18:21]
	s_add_i32 s53, s53, 2
	s_add_u32 s34, s34, 0x100
	s_addc_u32 s35, s35, 0
	s_add_u32 s51, s51, 0x100
	s_addc_u32 s52, s52, 0
	s_cmp_gt_u32 s53, 13
	v_mfma_f32_16x16x32_bf16 v[14:17], v[230:233], v[190:193], v[14:17]
	v_mfma_f32_16x16x32_bf16 v[10:13], v[242:245], v[190:193], v[10:13]
	v_mfma_f32_16x16x32_bf16 v[6:9], v[230:233], v[198:201], v[6:9]
	v_mfma_f32_16x16x32_bf16 v[2:5], v[242:245], v[198:201], v[2:5]
	s_barrier
	s_cbranch_scc0 .LBB0_104

.LBB0_181:
	s_add_i32 s88, s44, -2
	s_add_u32 s34, s34, 0x80
	s_addc_u32 s35, s35, 0
	s_add_u32 s89, s42, 0x100
	v_mov_b32_e32 v2, 0
	s_addc_u32 s90, s43, 0
	s_mov_b32 s2, 0
	s_add_i32 s91, s2, 2
	s_add_u32 s12, s34, 0x80
	s_addc_u32 s3, s35, 0
	s_add_i32 s13, 0, 0x10000
	v_add_u32_e32 v142, s13, v183
	ds_read_b128 v[130:133], v142
	ds_read_b128 v[134:137], v142 offset:1024
	ds_read_b128 v[138:141], v142 offset:2048
	ds_read_b128 v[142:145], v142 offset:3072
	s_cmp_eq_u32 s88, s2
	s_cselect_b32 s2, s0, s12
	s_cselect_b32 s3, s1, s3
	s_cselect_b32 s43, s41, s90
	s_cselect_b32 s42, s40, s89
	v_lshl_add_u64 v[190:191], s[34:35], 0, v[174:175]
	s_add_i32 m0, s55, 0xc000
	ds_read_b128 v[146:149], v184
	ds_read_b128 v[150:153], v184 offset:1024
	ds_read_b128 v[154:157], v184 offset:2048
	ds_read_b128 v[158:161], v184 offset:3072
	ds_read_b128 v[162:165], v184 offset:4096
	ds_read_b128 v[166:169], v184 offset:5120
	ds_read_b128 v[178:181], v184 offset:6144
	ds_read_b128 v[186:189], v184 offset:7168
	global_load_lds_dwordx4 v[190:191], off
	v_lshl_add_u64 v[190:191], s[34:35], 0, v[176:177]
	s_add_i32 m0, s55, 0xe000
	s_nop 0
	global_load_lds_dwordx4 v[190:191], off
	s_waitcnt lgkmcnt(8)
	s_add_i32 s92, 0, 0x14000
	s_add_i32 s12, s13, s54
	v_add_u32_e32 v185, s92, v183
	ds_read_b128 v[190:193], v185
	ds_read_b128 v[194:197], v185 offset:1024
	ds_read_b128 v[198:201], v185 offset:2048
	ds_read_b128 v[226:229], v185 offset:3072
	s_waitcnt lgkmcnt(0)
	s_barrier
	v_mfma_f32_16x16x32_bf16 v[126:129], v[130:133], v[146:149], 0
	v_mfma_f32_16x16x32_bf16 v[122:125], v[138:141], v[146:149], 0
	v_mfma_f32_16x16x32_bf16 v[118:121], v[130:133], v[154:157], 0
	v_mfma_f32_16x16x32_bf16 v[114:117], v[138:141], v[154:157], 0
	v_mfma_f32_16x16x32_bf16 v[110:113], v[130:133], v[162:165], 0
	v_mfma_f32_16x16x32_bf16 v[106:109], v[138:141], v[162:165], 0
	v_mfma_f32_16x16x32_bf16 v[102:105], v[130:133], v[178:181], 0
	v_mfma_f32_16x16x32_bf16 v[98:101], v[138:141], v[178:181], 0
	v_mfma_f32_16x16x32_bf16 v[126:129], v[134:137], v[150:153], v[126:129]
	v_mfma_f32_16x16x32_bf16 v[122:125], v[142:145], v[150:153], v[122:125]
	v_mfma_f32_16x16x32_bf16 v[118:121], v[134:137], v[158:161], v[118:121]
	v_mfma_f32_16x16x32_bf16 v[114:117], v[142:145], v[158:161], v[114:117]
	v_mfma_f32_16x16x32_bf16 v[110:113], v[134:137], v[166:169], v[110:113]
	v_mfma_f32_16x16x32_bf16 v[106:109], v[142:145], v[166:169], v[106:109]
	v_mfma_f32_16x16x32_bf16 v[102:105], v[134:137], v[186:189], v[102:105]
	v_mfma_f32_16x16x32_bf16 v[98:101], v[142:145], v[186:189], v[98:101]
	v_mfma_f32_16x16x32_bf16 v[62:65], v[190:193], v[146:149], 0
	v_mfma_f32_16x16x32_bf16 v[58:61], v[198:201], v[146:149], 0
	v_mfma_f32_16x16x32_bf16 v[54:57], v[190:193], v[154:157], 0
	v_mfma_f32_16x16x32_bf16 v[50:53], v[198:201], v[154:157], 0
	v_mfma_f32_16x16x32_bf16 v[46:49], v[190:193], v[162:165], 0
	v_mfma_f32_16x16x32_bf16 v[42:45], v[198:201], v[162:165], 0
	v_mfma_f32_16x16x32_bf16 v[38:41], v[190:193], v[178:181], 0
	v_mfma_f32_16x16x32_bf16 v[34:37], v[198:201], v[178:181], 0
	v_mfma_f32_16x16x32_bf16 v[62:65], v[194:197], v[150:153], v[62:65]
	v_mfma_f32_16x16x32_bf16 v[58:61], v[226:229], v[150:153], v[58:61]
	v_mfma_f32_16x16x32_bf16 v[54:57], v[194:197], v[158:161], v[54:57]
	v_mfma_f32_16x16x32_bf16 v[50:53], v[226:229], v[158:161], v[50:53]
	s_mov_b32 m0, s55
	v_lshl_add_u64 v[234:235], s[2:3], 0, v[170:171]
	v_mfma_f32_16x16x32_bf16 v[46:49], v[194:197], v[166:169], v[46:49]
	v_mfma_f32_16x16x32_bf16 v[42:45], v[226:229], v[166:169], v[42:45]
	v_mfma_f32_16x16x32_bf16 v[38:41], v[194:197], v[186:189], v[38:41]
	v_mfma_f32_16x16x32_bf16 v[34:37], v[226:229], v[186:189], v[34:37]
	s_barrier
	ds_read_b128 v[146:149], v184 offset:16384
	ds_read_b128 v[150:153], v184 offset:17408
	ds_read_b128 v[154:157], v184 offset:18432
	ds_read_b128 v[158:161], v184 offset:19456
	ds_read_b128 v[162:165], v184 offset:20480
	ds_read_b128 v[166:169], v184 offset:21504
	ds_read_b128 v[178:181], v184 offset:22528
	ds_read_b128 v[186:189], v184 offset:23552
	global_load_lds_dwordx4 v[234:235], off
	v_lshl_add_u64 v[236:237], s[2:3], 0, v[172:173]
	s_mov_b32 m0, s58
	s_nop 0
	global_load_lds_dwordx4 v[236:237], off
	v_lshl_add_u64 v[230:231], s[42:43], 0, v[170:171]
	s_mov_b32 m0, s12
	s_nop 0
	global_load_lds_dwordx4 v[230:231], off
	v_lshl_add_u64 v[232:233], s[42:43], 0, v[172:173]
	s_add_i32 m0, s12, 0x2000
	s_nop 0
	global_load_lds_dwordx4 v[232:233], off
	s_add_u32 s12, s42, s18
	s_addc_u32 s13, s43, 0
	s_add_i32 s42, s92, s54
	v_lshl_add_u64 v[242:243], s[12:13], 0, v[170:171]
	s_mov_b32 m0, s42
	v_lshl_add_u64 v[244:245], s[12:13], 0, v[172:173]
	global_load_lds_dwordx4 v[242:243], off
	s_add_i32 m0, s42, 0x2000
	s_nop 0
	global_load_lds_dwordx4 v[244:245], off
	s_waitcnt vmcnt(6)
	s_waitcnt lgkmcnt(0)
	s_barrier
	s_nop 0
	v_mfma_f32_16x16x32_bf16 v[94:97], v[130:133], v[146:149], 0
	v_mfma_f32_16x16x32_bf16 v[90:93], v[138:141], v[146:149], 0
	v_mfma_f32_16x16x32_bf16 v[86:89], v[130:133], v[154:157], 0
	v_mfma_f32_16x16x32_bf16 v[82:85], v[138:141], v[154:157], 0
	v_mfma_f32_16x16x32_bf16 v[78:81], v[130:133], v[162:165], 0
	v_mfma_f32_16x16x32_bf16 v[74:77], v[138:141], v[162:165], 0
	v_mfma_f32_16x16x32_bf16 v[70:73], v[130:133], v[178:181], 0
	v_mfma_f32_16x16x32_bf16 v[66:69], v[138:141], v[178:181], 0
	v_mfma_f32_16x16x32_bf16 v[94:97], v[134:137], v[150:153], v[94:97]
	v_mfma_f32_16x16x32_bf16 v[90:93], v[142:145], v[150:153], v[90:93]
	v_mfma_f32_16x16x32_bf16 v[86:89], v[134:137], v[158:161], v[86:89]
	v_mfma_f32_16x16x32_bf16 v[82:85], v[142:145], v[158:161], v[82:85]
	v_mfma_f32_16x16x32_bf16 v[78:81], v[134:137], v[166:169], v[78:81]
	v_mfma_f32_16x16x32_bf16 v[74:77], v[142:145], v[166:169], v[74:77]
	v_mfma_f32_16x16x32_bf16 v[70:73], v[134:137], v[186:189], v[70:73]
	v_mfma_f32_16x16x32_bf16 v[66:69], v[142:145], v[186:189], v[66:69]
	v_mfma_f32_16x16x32_bf16 v[30:33], v[190:193], v[146:149], 0
	v_mfma_f32_16x16x32_bf16 v[26:29], v[198:201], v[146:149], 0
	v_mfma_f32_16x16x32_bf16 v[22:25], v[190:193], v[154:157], 0
	v_mfma_f32_16x16x32_bf16 v[18:21], v[198:201], v[154:157], 0
	v_mfma_f32_16x16x32_bf16 v[14:17], v[190:193], v[162:165], 0
	v_mfma_f32_16x16x32_bf16 v[10:13], v[198:201], v[162:165], 0
	v_mfma_f32_16x16x32_bf16 v[6:9], v[190:193], v[178:181], 0
	v_mfma_f32_16x16x32_bf16 v[2:5], v[198:201], v[178:181], 0
	v_mfma_f32_16x16x32_bf16 v[30:33], v[194:197], v[150:153], v[30:33]
	v_mfma_f32_16x16x32_bf16 v[26:29], v[226:229], v[150:153], v[26:29]
	v_mfma_f32_16x16x32_bf16 v[22:25], v[194:197], v[158:161], v[22:25]
	v_mfma_f32_16x16x32_bf16 v[18:21], v[226:229], v[158:161], v[18:21]
	s_add_i32 s12, 0, 0x18000
	v_add_u32_e32 v142, s12, v183
	v_mfma_f32_16x16x32_bf16 v[14:17], v[194:197], v[166:169], v[14:17]
	v_mfma_f32_16x16x32_bf16 v[10:13], v[226:229], v[166:169], v[10:13]
	v_mfma_f32_16x16x32_bf16 v[6:9], v[194:197], v[186:189], v[6:9]
	v_mfma_f32_16x16x32_bf16 v[2:5], v[226:229], v[186:189], v[2:5]
	s_barrier
	ds_read_b128 v[130:133], v142
	ds_read_b128 v[134:137], v142 offset:1024
	ds_read_b128 v[138:141], v142 offset:2048
	ds_read_b128 v[142:145], v142 offset:3072
	s_add_u32 s2, s2, s18
	s_addc_u32 s3, s3, 0
	s_mov_b32 m0, s59
	v_lshl_add_u64 v[190:191], s[2:3], 0, v[170:171]
	ds_read_b128 v[146:149], v184 offset:32768
	ds_read_b128 v[150:153], v184 offset:33792
	ds_read_b128 v[154:157], v184 offset:34816
	ds_read_b128 v[158:161], v184 offset:35840
	ds_read_b128 v[162:165], v184 offset:36864
	ds_read_b128 v[166:169], v184 offset:37888
	ds_read_b128 v[178:181], v184 offset:38912
	ds_read_b128 v[186:189], v184 offset:39936
	global_load_lds_dwordx4 v[190:191], off
	v_lshl_add_u64 v[190:191], s[2:3], 0, v[172:173]
	s_mov_b32 m0, s77
	s_nop 0
	global_load_lds_dwordx4 v[190:191], off
	s_waitcnt lgkmcnt(8)
	s_add_i32 s2, 0, 0x1c000
	s_add_i32 s3, s12, s54
	v_add_u32_e32 v185, s2, v183
	ds_read_b128 v[190:193], v185
	ds_read_b128 v[194:197], v185 offset:1024
	ds_read_b128 v[198:201], v185 offset:2048
	ds_read_b128 v[226:229], v185 offset:3072
	s_waitcnt lgkmcnt(0)
	s_barrier
	v_mfma_f32_16x16x32_bf16 v[126:129], v[130:133], v[146:149], v[126:129]
	v_mfma_f32_16x16x32_bf16 v[122:125], v[138:141], v[146:149], v[122:125]
	v_mfma_f32_16x16x32_bf16 v[118:121], v[130:133], v[154:157], v[118:121]
	v_mfma_f32_16x16x32_bf16 v[114:117], v[138:141], v[154:157], v[114:117]
	v_mfma_f32_16x16x32_bf16 v[110:113], v[130:133], v[162:165], v[110:113]
	v_mfma_f32_16x16x32_bf16 v[106:109], v[138:141], v[162:165], v[106:109]
	v_mfma_f32_16x16x32_bf16 v[102:105], v[130:133], v[178:181], v[102:105]
	v_mfma_f32_16x16x32_bf16 v[98:101], v[138:141], v[178:181], v[98:101]
	v_mfma_f32_16x16x32_bf16 v[126:129], v[134:137], v[150:153], v[126:129]
	v_mfma_f32_16x16x32_bf16 v[122:125], v[142:145], v[150:153], v[122:125]
	v_mfma_f32_16x16x32_bf16 v[118:121], v[134:137], v[158:161], v[118:121]
	v_mfma_f32_16x16x32_bf16 v[114:117], v[142:145], v[158:161], v[114:117]
	v_mfma_f32_16x16x32_bf16 v[110:113], v[134:137], v[166:169], v[110:113]
	v_mfma_f32_16x16x32_bf16 v[106:109], v[142:145], v[166:169], v[106:109]
	v_mfma_f32_16x16x32_bf16 v[102:105], v[134:137], v[186:189], v[102:105]
	v_mfma_f32_16x16x32_bf16 v[98:101], v[142:145], v[186:189], v[98:101]
	v_mfma_f32_16x16x32_bf16 v[62:65], v[190:193], v[146:149], v[62:65]
	v_mfma_f32_16x16x32_bf16 v[58:61], v[198:201], v[146:149], v[58:61]
	v_mfma_f32_16x16x32_bf16 v[54:57], v[190:193], v[154:157], v[54:57]
	v_mfma_f32_16x16x32_bf16 v[50:53], v[198:201], v[154:157], v[50:53]
	v_mfma_f32_16x16x32_bf16 v[46:49], v[190:193], v[162:165], v[46:49]
	v_mfma_f32_16x16x32_bf16 v[42:45], v[198:201], v[162:165], v[42:45]
	v_mfma_f32_16x16x32_bf16 v[38:41], v[190:193], v[178:181], v[38:41]
	v_mfma_f32_16x16x32_bf16 v[34:37], v[198:201], v[178:181], v[34:37]
	v_mfma_f32_16x16x32_bf16 v[62:65], v[194:197], v[150:153], v[62:65]
	v_mfma_f32_16x16x32_bf16 v[58:61], v[226:229], v[150:153], v[58:61]
	v_mfma_f32_16x16x32_bf16 v[54:57], v[194:197], v[158:161], v[54:57]
	v_mfma_f32_16x16x32_bf16 v[50:53], v[226:229], v[158:161], v[50:53]
	s_mov_b32 m0, s80
	v_lshl_add_u64 v[234:235], v[234:235], 0, s[20:21]
	v_mfma_f32_16x16x32_bf16 v[46:49], v[194:197], v[166:169], v[46:49]
	v_mfma_f32_16x16x32_bf16 v[42:45], v[226:229], v[166:169], v[42:45]
	v_mfma_f32_16x16x32_bf16 v[38:41], v[194:197], v[186:189], v[38:41]
	v_mfma_f32_16x16x32_bf16 v[34:37], v[226:229], v[186:189], v[34:37]
	s_barrier
	ds_read_b128 v[146:149], v184 offset:49152
	ds_read_b128 v[150:153], v184 offset:50176
	ds_read_b128 v[154:157], v184 offset:51200
	ds_read_b128 v[158:161], v184 offset:52224
	ds_read_b128 v[162:165], v184 offset:53248
	ds_read_b128 v[166:169], v184 offset:54272
	ds_read_b128 v[178:181], v184 offset:55296
	ds_read_b128 v[186:189], v184 offset:56320
	global_load_lds_dwordx4 v[234:235], off
	v_lshl_add_u64 v[236:237], v[236:237], 0, s[20:21]
	s_mov_b32 m0, s81
	s_nop 0
	global_load_lds_dwordx4 v[236:237], off
	v_lshl_add_u64 v[230:231], v[230:231], 0, s[20:21]
	s_mov_b32 m0, s3
	s_nop 0
	global_load_lds_dwordx4 v[230:231], off
	v_lshl_add_u64 v[230:231], v[232:233], 0, s[20:21]
	s_add_i32 m0, s3, 0x2000
	s_nop 0
	global_load_lds_dwordx4 v[230:231], off
	s_add_i32 s2, s2, s54
	v_lshl_add_u64 v[242:243], v[242:243], 0, s[20:21]
	s_mov_b32 m0, s2
	s_nop 0
	global_load_lds_dwordx4 v[242:243], off
	v_lshl_add_u64 v[244:245], v[244:245], 0, s[20:21]
	s_add_i32 m0, s2, 0x2000
	s_nop 0
	global_load_lds_dwordx4 v[244:245], off
	s_waitcnt vmcnt(6)
	s_waitcnt lgkmcnt(0)
	s_barrier
	v_mfma_f32_16x16x32_bf16 v[94:97], v[130:133], v[146:149], v[94:97]
	v_mfma_f32_16x16x32_bf16 v[90:93], v[138:141], v[146:149], v[90:93]
	v_mfma_f32_16x16x32_bf16 v[86:89], v[130:133], v[154:157], v[86:89]
	v_mfma_f32_16x16x32_bf16 v[82:85], v[138:141], v[154:157], v[82:85]
	v_mfma_f32_16x16x32_bf16 v[78:81], v[130:133], v[162:165], v[78:81]
	v_mfma_f32_16x16x32_bf16 v[74:77], v[138:141], v[162:165], v[74:77]
	v_mfma_f32_16x16x32_bf16 v[70:73], v[130:133], v[178:181], v[70:73]
	v_mfma_f32_16x16x32_bf16 v[66:69], v[138:141], v[178:181], v[66:69]
	v_mfma_f32_16x16x32_bf16 v[94:97], v[134:137], v[150:153], v[94:97]
	v_mfma_f32_16x16x32_bf16 v[90:93], v[142:145], v[150:153], v[90:93]
	v_mfma_f32_16x16x32_bf16 v[86:89], v[134:137], v[158:161], v[86:89]
	v_mfma_f32_16x16x32_bf16 v[82:85], v[142:145], v[158:161], v[82:85]
	v_mfma_f32_16x16x32_bf16 v[78:81], v[134:137], v[166:169], v[78:81]
	v_mfma_f32_16x16x32_bf16 v[74:77], v[142:145], v[166:169], v[74:77]
	v_mfma_f32_16x16x32_bf16 v[70:73], v[134:137], v[186:189], v[70:73]
	v_mfma_f32_16x16x32_bf16 v[66:69], v[142:145], v[186:189], v[66:69]
	v_mfma_f32_16x16x32_bf16 v[30:33], v[190:193], v[146:149], v[30:33]
	v_mfma_f32_16x16x32_bf16 v[26:29], v[198:201], v[146:149], v[26:29]
	v_mfma_f32_16x16x32_bf16 v[22:25], v[190:193], v[154:157], v[22:25]
	v_mfma_f32_16x16x32_bf16 v[18:21], v[198:201], v[154:157], v[18:21]
	v_mfma_f32_16x16x32_bf16 v[14:17], v[190:193], v[162:165], v[14:17]
	v_mfma_f32_16x16x32_bf16 v[10:13], v[198:201], v[162:165], v[10:13]
	v_mfma_f32_16x16x32_bf16 v[6:9], v[190:193], v[178:181], v[6:9]
	v_mfma_f32_16x16x32_bf16 v[2:5], v[198:201], v[178:181], v[2:5]
	v_mfma_f32_16x16x32_bf16 v[30:33], v[194:197], v[150:153], v[30:33]
	v_mfma_f32_16x16x32_bf16 v[26:29], v[226:229], v[150:153], v[26:29]
	v_mfma_f32_16x16x32_bf16 v[22:25], v[194:197], v[158:161], v[22:25]
	v_mfma_f32_16x16x32_bf16 v[18:21], v[226:229], v[158:161], v[18:21]
	s_add_u32 s34, s34, 0x100
	s_addc_u32 s35, s35, 0
	s_add_u32 s89, s89, 0x100
	s_addc_u32 s90, s90, 0
	s_cmp_ge_i32 s91, s44
	s_mov_b32 s2, s91
	v_mfma_f32_16x16x32_bf16 v[14:17], v[194:197], v[166:169], v[14:17]
	v_mfma_f32_16x16x32_bf16 v[10:13], v[226:229], v[166:169], v[10:13]
	v_mfma_f32_16x16x32_bf16 v[6:9], v[194:197], v[186:189], v[6:9]
	v_mfma_f32_16x16x32_bf16 v[2:5], v[226:229], v[186:189], v[2:5]
	s_barrier
	s_cbranch_scc1 .Lpeel_x_1
.LBB0_182:
	s_add_i32 s91, s2, 2
	s_add_u32 s12, s34, 0x80
	s_addc_u32 s3, s35, 0
	s_add_i32 s13, 0, 0x10000
	v_add_u32_e32 v142, s13, v183
	ds_read_b128 v[130:133], v142
	ds_read_b128 v[134:137], v142 offset:1024
	ds_read_b128 v[138:141], v142 offset:2048
	ds_read_b128 v[142:145], v142 offset:3072
	s_cmp_eq_u32 s88, s2
	s_cselect_b32 s2, s0, s12
	s_cselect_b32 s3, s1, s3
	s_cselect_b32 s43, s41, s90
	s_cselect_b32 s42, s40, s89
	v_lshl_add_u64 v[190:191], s[34:35], 0, v[174:175]
	s_add_i32 m0, s55, 0xc000
	ds_read_b128 v[146:149], v184
	ds_read_b128 v[150:153], v184 offset:1024
	ds_read_b128 v[154:157], v184 offset:2048
	ds_read_b128 v[158:161], v184 offset:3072
	ds_read_b128 v[162:165], v184 offset:4096
	ds_read_b128 v[166:169], v184 offset:5120
	ds_read_b128 v[178:181], v184 offset:6144
	ds_read_b128 v[186:189], v184 offset:7168
	global_load_lds_dwordx4 v[190:191], off
	v_lshl_add_u64 v[190:191], s[34:35], 0, v[176:177]
	s_add_i32 m0, s55, 0xe000
	s_nop 0
	global_load_lds_dwordx4 v[190:191], off
	s_waitcnt lgkmcnt(8)
	s_add_i32 s92, 0, 0x14000
	s_add_i32 s12, s13, s54
	v_add_u32_e32 v185, s92, v183
	ds_read_b128 v[190:193], v185
	ds_read_b128 v[194:197], v185 offset:1024
	ds_read_b128 v[198:201], v185 offset:2048
	ds_read_b128 v[226:229], v185 offset:3072
	s_waitcnt lgkmcnt(0)
	s_barrier
	v_mfma_f32_16x16x32_bf16 v[126:129], v[130:133], v[146:149], v[126:129]
	v_mfma_f32_16x16x32_bf16 v[122:125], v[138:141], v[146:149], v[122:125]
	v_mfma_f32_16x16x32_bf16 v[118:121], v[130:133], v[154:157], v[118:121]
	v_mfma_f32_16x16x32_bf16 v[114:117], v[138:141], v[154:157], v[114:117]
	v_mfma_f32_16x16x32_bf16 v[110:113], v[130:133], v[162:165], v[110:113]
	v_mfma_f32_16x16x32_bf16 v[106:109], v[138:141], v[162:165], v[106:109]
	v_mfma_f32_16x16x32_bf16 v[102:105], v[130:133], v[178:181], v[102:105]
	v_mfma_f32_16x16x32_bf16 v[98:101], v[138:141], v[178:181], v[98:101]
	v_mfma_f32_16x16x32_bf16 v[126:129], v[134:137], v[150:153], v[126:129]
	v_mfma_f32_16x16x32_bf16 v[122:125], v[142:145], v[150:153], v[122:125]
	v_mfma_f32_16x16x32_bf16 v[118:121], v[134:137], v[158:161], v[118:121]
	v_mfma_f32_16x16x32_bf16 v[114:117], v[142:145], v[158:161], v[114:117]
	v_mfma_f32_16x16x32_bf16 v[110:113], v[134:137], v[166:169], v[110:113]
	v_mfma_f32_16x16x32_bf16 v[106:109], v[142:145], v[166:169], v[106:109]
	v_mfma_f32_16x16x32_bf16 v[102:105], v[134:137], v[186:189], v[102:105]
	v_mfma_f32_16x16x32_bf16 v[98:101], v[142:145], v[186:189], v[98:101]
	v_mfma_f32_16x16x32_bf16 v[62:65], v[190:193], v[146:149], v[62:65]
	v_mfma_f32_16x16x32_bf16 v[58:61], v[198:201], v[146:149], v[58:61]
	v_mfma_f32_16x16x32_bf16 v[54:57], v[190:193], v[154:157], v[54:57]
	v_mfma_f32_16x16x32_bf16 v[50:53], v[198:201], v[154:157], v[50:53]
	v_mfma_f32_16x16x32_bf16 v[46:49], v[190:193], v[162:165], v[46:49]
	v_mfma_f32_16x16x32_bf16 v[42:45], v[198:201], v[162:165], v[42:45]
	v_mfma_f32_16x16x32_bf16 v[38:41], v[190:193], v[178:181], v[38:41]
	v_mfma_f32_16x16x32_bf16 v[34:37], v[198:201], v[178:181], v[34:37]
	v_mfma_f32_16x16x32_bf16 v[62:65], v[194:197], v[150:153], v[62:65]
	v_mfma_f32_16x16x32_bf16 v[58:61], v[226:229], v[150:153], v[58:61]
	v_mfma_f32_16x16x32_bf16 v[54:57], v[194:197], v[158:161], v[54:57]
	v_mfma_f32_16x16x32_bf16 v[50:53], v[226:229], v[158:161], v[50:53]
	s_mov_b32 m0, s55
	v_lshl_add_u64 v[234:235], s[2:3], 0, v[170:171]
	v_mfma_f32_16x16x32_bf16 v[46:49], v[194:197], v[166:169], v[46:49]
	v_mfma_f32_16x16x32_bf16 v[42:45], v[226:229], v[166:169], v[42:45]
	v_mfma_f32_16x16x32_bf16 v[38:41], v[194:197], v[186:189], v[38:41]
	v_mfma_f32_16x16x32_bf16 v[34:37], v[226:229], v[186:189], v[34:37]
	s_barrier
	ds_read_b128 v[146:149], v184 offset:16384
	ds_read_b128 v[150:153], v184 offset:17408
	ds_read_b128 v[154:157], v184 offset:18432
	ds_read_b128 v[158:161], v184 offset:19456
	ds_read_b128 v[162:165], v184 offset:20480
	ds_read_b128 v[166:169], v184 offset:21504
	ds_read_b128 v[178:181], v184 offset:22528
	ds_read_b128 v[186:189], v184 offset:23552
	global_load_lds_dwordx4 v[234:235], off
	v_lshl_add_u64 v[236:237], s[2:3], 0, v[172:173]
	s_mov_b32 m0, s58
	s_nop 0
	global_load_lds_dwordx4 v[236:237], off
	v_lshl_add_u64 v[230:231], s[42:43], 0, v[170:171]
	s_mov_b32 m0, s12
	s_nop 0
	global_load_lds_dwordx4 v[230:231], off
	v_lshl_add_u64 v[232:233], s[42:43], 0, v[172:173]
	s_add_i32 m0, s12, 0x2000
	s_nop 0
	global_load_lds_dwordx4 v[232:233], off
	s_add_u32 s12, s42, s18
	s_addc_u32 s13, s43, 0
	s_add_i32 s42, s92, s54
	v_lshl_add_u64 v[242:243], s[12:13], 0, v[170:171]
	s_mov_b32 m0, s42
	v_lshl_add_u64 v[244:245], s[12:13], 0, v[172:173]
	global_load_lds_dwordx4 v[242:243], off
	s_add_i32 m0, s42, 0x2000
	s_nop 0
	global_load_lds_dwordx4 v[244:245], off
	s_waitcnt vmcnt(6)
	s_waitcnt lgkmcnt(0)
	s_barrier
	s_nop 0
	v_mfma_f32_16x16x32_bf16 v[94:97], v[130:133], v[146:149], v[94:97]
	v_mfma_f32_16x16x32_bf16 v[90:93], v[138:141], v[146:149], v[90:93]
	v_mfma_f32_16x16x32_bf16 v[86:89], v[130:133], v[154:157], v[86:89]
	v_mfma_f32_16x16x32_bf16 v[82:85], v[138:141], v[154:157], v[82:85]
	v_mfma_f32_16x16x32_bf16 v[78:81], v[130:133], v[162:165], v[78:81]
	v_mfma_f32_16x16x32_bf16 v[74:77], v[138:141], v[162:165], v[74:77]
	v_mfma_f32_16x16x32_bf16 v[70:73], v[130:133], v[178:181], v[70:73]
	v_mfma_f32_16x16x32_bf16 v[66:69], v[138:141], v[178:181], v[66:69]
	v_mfma_f32_16x16x32_bf16 v[94:97], v[134:137], v[150:153], v[94:97]
	v_mfma_f32_16x16x32_bf16 v[90:93], v[142:145], v[150:153], v[90:93]
	v_mfma_f32_16x16x32_bf16 v[86:89], v[134:137], v[158:161], v[86:89]
	v_mfma_f32_16x16x32_bf16 v[82:85], v[142:145], v[158:161], v[82:85]
	v_mfma_f32_16x16x32_bf16 v[78:81], v[134:137], v[166:169], v[78:81]
	v_mfma_f32_16x16x32_bf16 v[74:77], v[142:145], v[166:169], v[74:77]
	v_mfma_f32_16x16x32_bf16 v[70:73], v[134:137], v[186:189], v[70:73]
	v_mfma_f32_16x16x32_bf16 v[66:69], v[142:145], v[186:189], v[66:69]
	v_mfma_f32_16x16x32_bf16 v[30:33], v[190:193], v[146:149], v[30:33]
	v_mfma_f32_16x16x32_bf16 v[26:29], v[198:201], v[146:149], v[26:29]
	v_mfma_f32_16x16x32_bf16 v[22:25], v[190:193], v[154:157], v[22:25]
	v_mfma_f32_16x16x32_bf16 v[18:21], v[198:201], v[154:157], v[18:21]
	v_mfma_f32_16x16x32_bf16 v[14:17], v[190:193], v[162:165], v[14:17]
	v_mfma_f32_16x16x32_bf16 v[10:13], v[198:201], v[162:165], v[10:13]
	v_mfma_f32_16x16x32_bf16 v[6:9], v[190:193], v[178:181], v[6:9]
	v_mfma_f32_16x16x32_bf16 v[2:5], v[198:201], v[178:181], v[2:5]
	v_mfma_f32_16x16x32_bf16 v[30:33], v[194:197], v[150:153], v[30:33]
	v_mfma_f32_16x16x32_bf16 v[26:29], v[226:229], v[150:153], v[26:29]
	v_mfma_f32_16x16x32_bf16 v[22:25], v[194:197], v[158:161], v[22:25]
	v_mfma_f32_16x16x32_bf16 v[18:21], v[226:229], v[158:161], v[18:21]
	s_add_i32 s12, 0, 0x18000
	v_add_u32_e32 v142, s12, v183
	v_mfma_f32_16x16x32_bf16 v[14:17], v[194:197], v[166:169], v[14:17]
	v_mfma_f32_16x16x32_bf16 v[10:13], v[226:229], v[166:169], v[10:13]
	v_mfma_f32_16x16x32_bf16 v[6:9], v[194:197], v[186:189], v[6:9]
	v_mfma_f32_16x16x32_bf16 v[2:5], v[226:229], v[186:189], v[2:5]
	s_barrier
	ds_read_b128 v[130:133], v142
	ds_read_b128 v[134:137], v142 offset:1024
	ds_read_b128 v[138:141], v142 offset:2048
	ds_read_b128 v[142:145], v142 offset:3072
	s_add_u32 s2, s2, s18
	s_addc_u32 s3, s3, 0
	s_mov_b32 m0, s59
	v_lshl_add_u64 v[190:191], s[2:3], 0, v[170:171]
	ds_read_b128 v[146:149], v184 offset:32768
	ds_read_b128 v[150:153], v184 offset:33792
	ds_read_b128 v[154:157], v184 offset:34816
	ds_read_b128 v[158:161], v184 offset:35840
	ds_read_b128 v[162:165], v184 offset:36864
	ds_read_b128 v[166:169], v184 offset:37888
	ds_read_b128 v[178:181], v184 offset:38912
	ds_read_b128 v[186:189], v184 offset:39936
	global_load_lds_dwordx4 v[190:191], off
	v_lshl_add_u64 v[190:191], s[2:3], 0, v[172:173]
	s_mov_b32 m0, s77
	s_nop 0
	global_load_lds_dwordx4 v[190:191], off
	s_waitcnt lgkmcnt(8)
	s_add_i32 s2, 0, 0x1c000
	s_add_i32 s3, s12, s54
	v_add_u32_e32 v185, s2, v183
	ds_read_b128 v[190:193], v185
	ds_read_b128 v[194:197], v185 offset:1024
	ds_read_b128 v[198:201], v185 offset:2048
	ds_read_b128 v[226:229], v185 offset:3072
	s_waitcnt lgkmcnt(0)
	s_barrier
	v_mfma_f32_16x16x32_bf16 v[126:129], v[130:133], v[146:149], v[126:129]
	v_mfma_f32_16x16x32_bf16 v[122:125], v[138:141], v[146:149], v[122:125]
	v_mfma_f32_16x16x32_bf16 v[118:121], v[130:133], v[154:157], v[118:121]
	v_mfma_f32_16x16x32_bf16 v[114:117], v[138:141], v[154:157], v[114:117]
	v_mfma_f32_16x16x32_bf16 v[110:113], v[130:133], v[162:165], v[110:113]
	v_mfma_f32_16x16x32_bf16 v[106:109], v[138:141], v[162:165], v[106:109]
	v_mfma_f32_16x16x32_bf16 v[102:105], v[130:133], v[178:181], v[102:105]
	v_mfma_f32_16x16x32_bf16 v[98:101], v[138:141], v[178:181], v[98:101]
	v_mfma_f32_16x16x32_bf16 v[126:129], v[134:137], v[150:153], v[126:129]
	v_mfma_f32_16x16x32_bf16 v[122:125], v[142:145], v[150:153], v[122:125]
	v_mfma_f32_16x16x32_bf16 v[118:121], v[134:137], v[158:161], v[118:121]
	v_mfma_f32_16x16x32_bf16 v[114:117], v[142:145], v[158:161], v[114:117]
	v_mfma_f32_16x16x32_bf16 v[110:113], v[134:137], v[166:169], v[110:113]
	v_mfma_f32_16x16x32_bf16 v[106:109], v[142:145], v[166:169], v[106:109]
	v_mfma_f32_16x16x32_bf16 v[102:105], v[134:137], v[186:189], v[102:105]
	v_mfma_f32_16x16x32_bf16 v[98:101], v[142:145], v[186:189], v[98:101]
	v_mfma_f32_16x16x32_bf16 v[62:65], v[190:193], v[146:149], v[62:65]
	v_mfma_f32_16x16x32_bf16 v[58:61], v[198:201], v[146:149], v[58:61]
	v_mfma_f32_16x16x32_bf16 v[54:57], v[190:193], v[154:157], v[54:57]
	v_mfma_f32_16x16x32_bf16 v[50:53], v[198:201], v[154:157], v[50:53]
	v_mfma_f32_16x16x32_bf16 v[46:49], v[190:193], v[162:165], v[46:49]
	v_mfma_f32_16x16x32_bf16 v[42:45], v[198:201], v[162:165], v[42:45]
	v_mfma_f32_16x16x32_bf16 v[38:41], v[190:193], v[178:181], v[38:41]
	v_mfma_f32_16x16x32_bf16 v[34:37], v[198:201], v[178:181], v[34:37]
	v_mfma_f32_16x16x32_bf16 v[62:65], v[194:197], v[150:153], v[62:65]
	v_mfma_f32_16x16x32_bf16 v[58:61], v[226:229], v[150:153], v[58:61]
	v_mfma_f32_16x16x32_bf16 v[54:57], v[194:197], v[158:161], v[54:57]
	v_mfma_f32_16x16x32_bf16 v[50:53], v[226:229], v[158:161], v[50:53]
	s_mov_b32 m0, s80
	v_lshl_add_u64 v[234:235], v[234:235], 0, s[20:21]
	v_mfma_f32_16x16x32_bf16 v[46:49], v[194:197], v[166:169], v[46:49]
	v_mfma_f32_16x16x32_bf16 v[42:45], v[226:229], v[166:169], v[42:45]
	v_mfma_f32_16x16x32_bf16 v[38:41], v[194:197], v[186:189], v[38:41]
	v_mfma_f32_16x16x32_bf16 v[34:37], v[226:229], v[186:189], v[34:37]
	s_barrier
	ds_read_b128 v[146:149], v184 offset:49152
	ds_read_b128 v[150:153], v184 offset:50176
	ds_read_b128 v[154:157], v184 offset:51200
	ds_read_b128 v[158:161], v184 offset:52224
	ds_read_b128 v[162:165], v184 offset:53248
	ds_read_b128 v[166:169], v184 offset:54272
	ds_read_b128 v[178:181], v184 offset:55296
	ds_read_b128 v[186:189], v184 offset:56320
	global_load_lds_dwordx4 v[234:235], off
	v_lshl_add_u64 v[236:237], v[236:237], 0, s[20:21]
	s_mov_b32 m0, s81
	s_nop 0
	global_load_lds_dwordx4 v[236:237], off
	v_lshl_add_u64 v[230:231], v[230:231], 0, s[20:21]
	s_mov_b32 m0, s3
	s_nop 0
	global_load_lds_dwordx4 v[230:231], off
	v_lshl_add_u64 v[230:231], v[232:233], 0, s[20:21]
	s_add_i32 m0, s3, 0x2000
	s_nop 0
	global_load_lds_dwordx4 v[230:231], off
	s_add_i32 s2, s2, s54
	v_lshl_add_u64 v[242:243], v[242:243], 0, s[20:21]
	s_mov_b32 m0, s2
	s_nop 0
	global_load_lds_dwordx4 v[242:243], off
	v_lshl_add_u64 v[244:245], v[244:245], 0, s[20:21]
	s_add_i32 m0, s2, 0x2000
	s_nop 0
	global_load_lds_dwordx4 v[244:245], off
	s_waitcnt vmcnt(6)
	s_waitcnt lgkmcnt(0)
	s_barrier
	v_mfma_f32_16x16x32_bf16 v[94:97], v[130:133], v[146:149], v[94:97]
	v_mfma_f32_16x16x32_bf16 v[90:93], v[138:141], v[146:149], v[90:93]
	v_mfma_f32_16x16x32_bf16 v[86:89], v[130:133], v[154:157], v[86:89]
	v_mfma_f32_16x16x32_bf16 v[82:85], v[138:141], v[154:157], v[82:85]
	v_mfma_f32_16x16x32_bf16 v[78:81], v[130:133], v[162:165], v[78:81]
	v_mfma_f32_16x16x32_bf16 v[74:77], v[138:141], v[162:165], v[74:77]
	v_mfma_f32_16x16x32_bf16 v[70:73], v[130:133], v[178:181], v[70:73]
	v_mfma_f32_16x16x32_bf16 v[66:69], v[138:141], v[178:181], v[66:69]
	v_mfma_f32_16x16x32_bf16 v[94:97], v[134:137], v[150:153], v[94:97]
	v_mfma_f32_16x16x32_bf16 v[90:93], v[142:145], v[150:153], v[90:93]
	v_mfma_f32_16x16x32_bf16 v[86:89], v[134:137], v[158:161], v[86:89]
	v_mfma_f32_16x16x32_bf16 v[82:85], v[142:145], v[158:161], v[82:85]
	v_mfma_f32_16x16x32_bf16 v[78:81], v[134:137], v[166:169], v[78:81]
	v_mfma_f32_16x16x32_bf16 v[74:77], v[142:145], v[166:169], v[74:77]
	v_mfma_f32_16x16x32_bf16 v[70:73], v[134:137], v[186:189], v[70:73]
	v_mfma_f32_16x16x32_bf16 v[66:69], v[142:145], v[186:189], v[66:69]
	v_mfma_f32_16x16x32_bf16 v[30:33], v[190:193], v[146:149], v[30:33]
	v_mfma_f32_16x16x32_bf16 v[26:29], v[198:201], v[146:149], v[26:29]
	v_mfma_f32_16x16x32_bf16 v[22:25], v[190:193], v[154:157], v[22:25]
	v_mfma_f32_16x16x32_bf16 v[18:21], v[198:201], v[154:157], v[18:21]
	v_mfma_f32_16x16x32_bf16 v[14:17], v[190:193], v[162:165], v[14:17]
	v_mfma_f32_16x16x32_bf16 v[10:13], v[198:201], v[162:165], v[10:13]
	v_mfma_f32_16x16x32_bf16 v[6:9], v[190:193], v[178:181], v[6:9]
	v_mfma_f32_16x16x32_bf16 v[2:5], v[198:201], v[178:181], v[2:5]
	v_mfma_f32_16x16x32_bf16 v[30:33], v[194:197], v[150:153], v[30:33]
	v_mfma_f32_16x16x32_bf16 v[26:29], v[226:229], v[150:153], v[26:29]
	v_mfma_f32_16x16x32_bf16 v[22:25], v[194:197], v[158:161], v[22:25]
	v_mfma_f32_16x16x32_bf16 v[18:21], v[226:229], v[158:161], v[18:21]
	s_add_u32 s34, s34, 0x100
	s_addc_u32 s35, s35, 0
	s_add_u32 s89, s89, 0x100
	s_addc_u32 s90, s90, 0
	s_cmp_ge_i32 s91, s44
	s_mov_b32 s2, s91
	v_mfma_f32_16x16x32_bf16 v[14:17], v[194:197], v[166:169], v[14:17]
	v_mfma_f32_16x16x32_bf16 v[10:13], v[226:229], v[166:169], v[10:13]
	v_mfma_f32_16x16x32_bf16 v[6:9], v[194:197], v[186:189], v[6:9]
	v_mfma_f32_16x16x32_bf16 v[2:5], v[226:229], v[186:189], v[2:5]
	s_barrier
	s_cbranch_scc0 .LBB0_182
